# transmul: x1h/conv-weight loads of a tile issued together with its Yp loads (one memory round trip per tile instead of two)
# speedup vs baseline: 1.0258x; 1.0006x over previous
; __device__ __forceinline__ int get_bid() { return 2 * get_rbid() + get_hb(); }
; __device__ __forceinline__ void phase_transmul(CP& p, char* smem) {
;     ...
;   for (int it = get_bid(); it < 4096; it += VGRID) {
;     const int ct = it & 15, rt = it >> 4;
;     const int c0 = ct * 64, r0 = rt * 64;
;     __syncthreads();
; #pragma unroll
;     for (int i = 0; i < 2; ++i) {
;       const int ci = tid + 256 * i; const int cc = ci >> 3, ch = ci & 7;
;       const uint4 u = *(const uint4*)(p.Yp + (size_t)(c0 + cc) * 16384 + r0 + ch * 8);
;       unsigned* d = (unsigned*)(tl + cc * 66 + ch * 8);
;       d[0] = u.x; d[1] = u.y; d[2] = u.z; d[3] = u.w;
;     }
;     __syncthreads();
;     const int row = tid >> 2, cq = tid & 3;
;     const int grow = r0 + row, pos = grow & 2047;
;     const int cbase = c0 + cq * 16;
;     const bf16_t* xp = p.x1h + (size_t)grow * 1024 + cbase;
;     uint4 zero4; zero4.x = 0; zero4.y = 0; zero4.z = 0; zero4.w = 0;
;     const uint4 xa = *(const uint4*)xp, xb = *(const uint4*)(xp + 8);
;     const bf16_t* xpp = pos > 0 ? xp - 1024 : xp;
;     const bf16_t* xpn = pos < 2047 ? xp + 1024 : xp;
;     const float pmk = pos > 0 ? 1.f : 0.f, nmk = pos < 2047 ? 1.f : 0.f;
;     const uint4 pa = *(const uint4*)xpp, pb = *(const uint4*)(xpp + 8);
;     const uint4 na = *(const uint4*)xpn, nb = *(const uint4*)(xpn + 8);
;     (void)zero4;
;     const unsigned xs[8] = {xa.x, xa.y, xa.z, xa.w, xb.x, xb.y, xb.z, xb.w};
;     const unsigned ps[8] = {pa.x, pa.y, pa.z, pa.w, pb.x, pb.y, pb.z, pb.w};
;     const unsigned ns[8] = {na.x, na.y, na.z, na.w, nb.x, nb.y, nb.z, nb.w};
;     unsigned o[8];
; #pragma unroll
;     for (int j4 = 0; j4 < 4; ++j4) {
;       const f32x4 w0 = *(const f32x4*)(p.hy_conv_w + cbase + 4 * j4) * pmk, w1 = *(const f32x4*)(p.hy_conv_w + 3072 + cbase + 4 * j4);
;       const f32x4 w2 = *(const f32x4*)(p.hy_conv_w + 2 * 3072 + cbase + 4 * j4) * nmk, wb = *(const f32x4*)(p.hy_conv_b + cbase + 4 * j4);
.LBB0_3032:
	s_and_b32 s18, s23, 0x3c0
	s_and_b32 s4, s21, 0xffffffc0
	v_add_u32_e32 v18, s18, v10
	s_ashr_i32 s5, s4, 31
	v_add_u32_e32 v20, s18, v11
	v_add_u32_e32 v22, s4, v7
	v_ashrrev_i32_e32 v19, 31, v18
	v_lshl_add_u64 v[24:25], s[4:5], 1, v[4:5]
	v_ashrrev_i32_e32 v21, 31, v20
	v_and_b32_e32 v28, 0x7ff, v22
	v_ashrrev_i32_e32 v23, 31, v22
	v_lshlrev_b64 v[18:19], 15, v[18:19]
	v_lshlrev_b64 v[20:21], 15, v[20:21]
	v_lshlrev_b64 v[22:23], 11, v[22:23]
	v_cmp_eq_u32_e32 vcc, 0, v28
	v_cmp_eq_u32_e64 s[4:5], s25, v28
	v_lshl_add_u64 v[28:29], v[24:25], 0, v[18:19]
	s_barrier
	v_lshl_add_u64 v[30:31], v[24:25], 0, v[20:21]
	v_lshl_add_u64 v[32:33], s[6:7], 0, v[22:23]
	v_lshl_add_u64 v[34:35], s[12:13], 0, v[22:23]
	global_load_dwordx4 v[142:145], v[28:29], off
	global_load_dwordx4 v[146:149], v[30:31], off
	v_or_b32_e32 v26, s18, v6
	v_lshlrev_b32_e32 v2, 1, v26
	s_lshl_b32 s18, s18, 1
	v_lshlrev_b32_e32 v107, 2, v26
	v_cndmask_b32_e64 v27, -1, 0, vcc
	v_cndmask_b32_e64 v26, v16, 0, vcc
	v_lshl_add_u64 v[78:79], v[32:33], 0, v[2:3]
	v_cndmask_b32_e64 v2, v17, 0, s[4:5]
	v_lshl_add_u64 v[28:29], v[34:35], 0, s[18:19]
	v_lshl_add_u64 v[80:81], v[78:79], 0, v[26:27]
	v_lshl_add_u64 v[82:83], v[78:79], 0, v[2:3]
	v_lshl_add_u64 v[110:111], v[28:29], 0, v[8:9]
	v_cndmask_b32_e64 v106, 1.0, 0, vcc
	v_cndmask_b32_e64 v108, 1.0, 0, s[4:5]
	s_add_i32 s3, s3, s20
	s_add_i32 s21, s21, s22
	s_add_i32 s23, s23, s24
	s_cmpk_lt_i32 s3, 0x1000
	global_load_dwordx4 v[18:21], v107, s[8:9]
	global_load_dwordx4 v[22:25], v107, s[16:17]
	global_load_dwordx4 v[26:29], v[80:81], off
	global_load_dwordx4 v[30:33], v[78:79], off
	global_load_dwordx4 v[34:37], v[82:83], off
	global_load_dwordx4 v[38:41], v107, s[8:9] offset:16
	global_load_dwordx4 v[42:45], v107, s[16:17] offset:16
	global_load_dwordx4 v[46:49], v107, s[8:9] offset:32
	global_load_dwordx4 v[50:53], v107, s[16:17] offset:32
	global_load_dwordx4 v[54:57], v[78:79], off offset:16
	global_load_dwordx4 v[58:61], v[80:81], off offset:16
	global_load_dwordx4 v[62:65], v[82:83], off offset:16
	global_load_dwordx4 v[66:69], v107, s[10:11]
	global_load_dwordx4 v[70:73], v107, s[14:15]
	global_load_dwordx4 v[74:77], v107, s[14:15] offset:16
	s_nop 0
	global_load_dwordx4 v[78:81], v107, s[10:11] offset:16
	global_load_dwordx4 v[82:85], v107, s[10:11] offset:32
	global_load_dwordx4 v[86:89], v107, s[14:15] offset:32
	global_load_dwordx4 v[90:93], v107, s[14:15] offset:48
	global_load_dwordx4 v[94:97], v107, s[16:17] offset:48
	global_load_dwordx4 v[98:101], v107, s[8:9] offset:48
	global_load_dwordx4 v[102:105], v107, s[10:11] offset:48
	s_waitcnt vmcnt(23)
	ds_write2_b32 v14, v142, v143 offset1:1
	ds_write2_b32 v14, v144, v145 offset0:2 offset1:3
	s_waitcnt vmcnt(22)
	ds_write2_b32 v15, v146, v147 offset1:1
	ds_write2_b32 v15, v148, v149 offset0:2 offset1:3
	s_waitcnt lgkmcnt(0)
	s_barrier
; __device__ __forceinline__ unsigned pack2(float a, float b) { unsigned r; asm("v_cvt_pk_bf16_f32 %0, %1, %2" : "=v"(r) : "v"(a), "v"(b)); return r; }
; __device__ __forceinline__ float bf2f(bf16_t h) { return __uint_as_float(((unsigned)h) << 16); }
; __device__ __forceinline__ void phase_transmul(CP& p, char* smem) {
;     ...
;     const unsigned xs[8] = {xa.x, xa.y, xa.z, xa.w, xb.x, xb.y, xb.z, xb.w};
;     const unsigned ps[8] = {pa.x, pa.y, pa.z, pa.w, pb.x, pb.y, pb.z, pb.w};
;     const unsigned ns[8] = {na.x, na.y, na.z, na.w, nb.x, nb.y, nb.z, nb.w};
;     unsigned o[8];
; #pragma unroll
;     for (int j4 = 0; j4 < 4; ++j4) {
;       const f32x4 w0 = *(const f32x4*)(p.hy_conv_w + cbase + 4 * j4) * pmk, w1 = *(const f32x4*)(p.hy_conv_w + 3072 + cbase + 4 * j4);
;       const f32x4 w2 = *(const f32x4*)(p.hy_conv_w + 2 * 3072 + cbase + 4 * j4) * nmk, wb = *(const f32x4*)(p.hy_conv_b + cbase + 4 * j4);
; #pragma unroll
;       for (int jj = 0; jj < 2; ++jj) {
;         const int j = 2 * j4 + jj;
;         const float x0 = w0[2 * jj] * __uint_as_float(ps[j] << 16) + w1[2 * jj] * __uint_as_float(xs[j] << 16) + w2[2 * jj] * __uint_as_float(ns[j] << 16) + wb[2 * jj];
;         const float x1 = w0[2 * jj + 1] * __uint_as_float(ps[j] & 0xffff0000u) + w1[2 * jj + 1] * __uint_as_float(xs[j] & 0xffff0000u) + w2[2 * jj + 1] * __uint_as_float(ns[j] & 0xffff0000u) + wb[2 * jj + 1];
;         const float y0 = bf2f(tl[(cq * 16 + 2 * j) * 66 + row]) * x0;
;         const float y1 = bf2f(tl[(cq * 16 + 2 * j + 1) * 66 + row]) * x1;
;         o[j] = pack2(y0, y1);
;       }
;     }
;     bf16_t* op = p.hxc + (size_t)(r0 + row) * 1024 + c0 + cq * 16;
;     uint4 oa; oa.x = o[0]; oa.y = o[1]; oa.z = o[2]; oa.w = o[3];
;     uint4 ob; ob.x = o[4]; ob.y = o[5]; ob.z = o[6]; ob.w = o[7];
;     *(uint4*)op = oa; *(uint4*)(op + 8) = ob;
	ds_read_u16 v2, v12
	ds_read_u16 v107, v12 offset:264
	ds_read_u16 v109, v12 offset:528
	ds_read_u16 v112, v12 offset:792
	ds_read_u16 v113, v12 offset:1056
	ds_read_u16 v114, v12 offset:1320
	ds_read_u16 v115, v12 offset:1584
	ds_read_u16 v116, v12 offset:1848
	ds_read_u16 v117, v13 offset:132
	ds_read_u16 v118, v13 offset:396
	ds_read_u16 v119, v13 offset:660
	ds_read_u16 v120, v13 offset:924
	ds_read_u16 v121, v13 offset:1188
	ds_read_u16 v122, v13 offset:1452
	ds_read_u16 v123, v13 offset:1716
	ds_read_u16 v124, v13 offset:1980
	s_waitcnt lgkmcnt(14)
	v_lshlrev_b32_e32 v107, 16, v107
	s_waitcnt lgkmcnt(13)
	v_lshlrev_b32_e32 v109, 16, v109
	v_lshlrev_b32_e32 v2, 16, v2
	s_waitcnt lgkmcnt(7)
	v_lshlrev_b32_e32 v117, 16, v117
	s_waitcnt lgkmcnt(6)
	v_lshlrev_b32_e32 v118, 16, v118
	s_waitcnt lgkmcnt(5)
	v_lshlrev_b32_e32 v119, 16, v119
	v_lshlrev_b32_e32 v112, 16, v112
	s_waitcnt lgkmcnt(4)
	v_lshlrev_b32_e32 v120, 16, v120
	v_lshlrev_b32_e32 v113, 16, v113
	s_waitcnt lgkmcnt(3)
	v_lshlrev_b32_e32 v121, 16, v121
	v_lshlrev_b32_e32 v114, 16, v114
	s_waitcnt lgkmcnt(2)
	v_lshlrev_b32_e32 v122, 16, v122
	v_lshlrev_b32_e32 v115, 16, v115
	s_waitcnt lgkmcnt(1)
	v_lshlrev_b32_e32 v123, 16, v123
	v_lshlrev_b32_e32 v116, 16, v116
	s_waitcnt lgkmcnt(0)
	v_lshlrev_b32_e32 v124, 16, v124
	s_waitcnt vmcnt(21)
	v_pk_mul_f32 v[20:21], v[106:107], v[20:21] op_sel_hi:[0,1]
	v_pk_mul_f32 v[18:19], v[106:107], v[18:19] op_sel_hi:[0,1]
	s_waitcnt vmcnt(19)
	v_lshlrev_b32_e32 v125, 16, v26
	s_waitcnt vmcnt(18)
	v_lshlrev_b32_e32 v126, 16, v30
	v_and_b32_e32 v129, 0xffff0000, v30
	v_lshlrev_b32_e32 v132, 16, v31
	v_and_b32_e32 v135, 0xffff0000, v31
	v_lshlrev_b32_e32 v138, 16, v32
	v_and_b32_e32 v128, 0xffff0000, v26
	v_lshlrev_b32_e32 v131, 16, v27
	v_and_b32_e32 v134, 0xffff0000, v27
	s_waitcnt vmcnt(16)
	v_pk_mul_f32 v[26:27], v[106:107], v[40:41] op_sel_hi:[0,1]
	v_pk_mul_f32 v[30:31], v[106:107], v[38:39] op_sel_hi:[0,1]
	v_lshlrev_b32_e32 v137, 16, v28
	v_and_b32_e32 v141, 0xffff0000, v32
	v_lshlrev_b32_e32 v144, 16, v33
	v_and_b32_e32 v147, 0xffff0000, v33
	s_waitcnt vmcnt(13)
	v_pk_mul_f32 v[40:41], v[108:109], v[50:51] op_sel_hi:[0,1]
	s_waitcnt vmcnt(12)
	v_lshlrev_b32_e32 v51, 16, v54
	s_waitcnt vmcnt(8)
	v_mul_f32_e32 v70, v70, v126
	v_mul_f32_e32 v71, v71, v129
	v_mul_f32_e32 v72, v72, v132
	v_mul_f32_e32 v73, v73, v135
	s_waitcnt vmcnt(7)
	v_mul_f32_e32 v74, v74, v138
	v_pk_mul_f32 v[24:25], v[108:109], v[24:25] op_sel_hi:[0,1]
	v_pk_mul_f32 v[22:23], v[108:109], v[22:23] op_sel_hi:[0,1]
	v_lshlrev_b32_e32 v127, 16, v34
	v_and_b32_e32 v130, 0xffff0000, v34
	v_lshlrev_b32_e32 v133, 16, v35
	v_and_b32_e32 v136, 0xffff0000, v35
	v_pk_mul_f32 v[34:35], v[108:109], v[44:45] op_sel_hi:[0,1]
	v_pk_mul_f32 v[38:39], v[108:109], v[42:43] op_sel_hi:[0,1]
	v_lshlrev_b32_e32 v139, 16, v36
	v_and_b32_e32 v140, 0xffff0000, v28
	v_lshlrev_b32_e32 v143, 16, v29
	v_and_b32_e32 v146, 0xffff0000, v29
	v_pk_mul_f32 v[28:29], v[106:107], v[48:49] op_sel_hi:[0,1]
	v_pk_mul_f32 v[32:33], v[106:107], v[46:47] op_sel_hi:[0,1]
	v_lshlrev_b32_e32 v50, 16, v58
	v_and_b32_e32 v54, 0xffff0000, v54
	v_lshlrev_b32_e32 v149, 16, v55
	v_and_b32_e32 v55, 0xffff0000, v55
	s_waitcnt vmcnt(1)
	v_pk_mul_f32 v[44:45], v[106:107], v[98:99] op_sel_hi:[0,1]
	v_pk_mul_f32 v[48:49], v[108:109], v[94:95] op_sel_hi:[0,1]
	v_lshlrev_b32_e32 v95, 16, v56
	v_and_b32_e32 v56, 0xffff0000, v56
	v_lshlrev_b32_e32 v98, 16, v57
	v_and_b32_e32 v57, 0xffff0000, v57
	v_mul_f32_e32 v75, v75, v141
	v_mul_f32_e32 v76, v76, v144
	v_mul_f32_e32 v77, v77, v147
	v_mul_f32_e32 v51, v86, v51
	v_fmac_f32_e32 v70, v18, v125
	v_fmac_f32_e32 v71, v19, v128
	v_fmac_f32_e32 v72, v20, v131
	v_fmac_f32_e32 v73, v21, v134
	v_fmac_f32_e32 v74, v30, v137
	v_and_b32_e32 v142, 0xffff0000, v36
	v_lshlrev_b32_e32 v145, 16, v37
	v_and_b32_e32 v148, 0xffff0000, v37
	v_pk_mul_f32 v[36:37], v[108:109], v[52:53] op_sel_hi:[0,1]
	v_lshlrev_b32_e32 v52, 16, v62
	v_and_b32_e32 v53, 0xffff0000, v58
	v_and_b32_e32 v58, 0xffff0000, v62
	v_lshlrev_b32_e32 v62, 16, v59
	v_and_b32_e32 v59, 0xffff0000, v59
	v_pk_mul_f32 v[42:43], v[106:107], v[100:101] op_sel_hi:[0,1]
	v_pk_mul_f32 v[46:47], v[108:109], v[96:97] op_sel_hi:[0,1]
	v_lshlrev_b32_e32 v94, 16, v60
	v_and_b32_e32 v60, 0xffff0000, v60
	v_lshlrev_b32_e32 v97, 16, v61
	v_and_b32_e32 v61, 0xffff0000, v61
	v_mul_f32_e32 v54, v87, v54
	v_mul_f32_e32 v86, v88, v149
	v_mul_f32_e32 v55, v89, v55
	v_mul_f32_e32 v87, v90, v95
	v_mul_f32_e32 v56, v91, v56
	v_mul_f32_e32 v88, v92, v98
	v_mul_f32_e32 v57, v93, v57
	v_fmac_f32_e32 v75, v31, v140
	v_fmac_f32_e32 v76, v26, v143
	v_fmac_f32_e32 v77, v27, v146
	v_fmac_f32_e32 v51, v32, v50
	v_fmac_f32_e32 v70, v22, v127
	v_fmac_f32_e32 v71, v23, v130
	v_fmac_f32_e32 v72, v24, v133
	v_fmac_f32_e32 v73, v25, v136
	v_fmac_f32_e32 v74, v38, v139
	v_lshlrev_b32_e32 v150, 16, v63
	v_and_b32_e32 v63, 0xffff0000, v63
	v_lshlrev_b32_e32 v96, 16, v64
	v_and_b32_e32 v64, 0xffff0000, v64
	v_lshlrev_b32_e32 v99, 16, v65
	v_and_b32_e32 v65, 0xffff0000, v65
	v_fmac_f32_e32 v54, v33, v53
	v_fmac_f32_e32 v86, v28, v62
	v_fmac_f32_e32 v55, v29, v59
	v_fmac_f32_e32 v87, v44, v94
	v_fmac_f32_e32 v56, v45, v60
	v_fmac_f32_e32 v88, v42, v97
	v_fmac_f32_e32 v57, v43, v61
	v_fmac_f32_e32 v75, v39, v142
	v_fmac_f32_e32 v76, v34, v145
	v_fmac_f32_e32 v77, v35, v148
	v_fmac_f32_e32 v51, v40, v52
	v_add_f32_e32 v18, v66, v70
	v_add_f32_e32 v19, v67, v71
	v_add_f32_e32 v20, v68, v72
	v_add_f32_e32 v21, v69, v73
	v_add_f32_e32 v22, v78, v74
	v_fmac_f32_e32 v54, v41, v58
	v_fmac_f32_e32 v86, v36, v150
	v_fmac_f32_e32 v55, v37, v63
	v_fmac_f32_e32 v87, v48, v96
	v_fmac_f32_e32 v56, v49, v64
	v_fmac_f32_e32 v88, v46, v99
	v_fmac_f32_e32 v57, v47, v65
	v_add_f32_e32 v23, v79, v75
	v_add_f32_e32 v24, v80, v76
	v_add_f32_e32 v25, v81, v77
	v_add_f32_e32 v26, v82, v51
	v_mul_f32_e32 v2, v18, v2
	v_mul_f32_e32 v18, v19, v117
	v_mul_f32_e32 v19, v20, v107
	v_mul_f32_e32 v20, v21, v118
	v_mul_f32_e32 v21, v22, v109
	v_add_f32_e32 v27, v83, v54
	v_add_f32_e32 v28, v84, v86
	v_add_f32_e32 v29, v85, v55
	s_waitcnt vmcnt(0)
	v_add_f32_e32 v30, v102, v87
	v_add_f32_e32 v31, v103, v56
	v_add_f32_e32 v32, v104, v88
	v_add_f32_e32 v33, v105, v57
	v_mul_f32_e32 v22, v23, v119
	v_mul_f32_e32 v23, v24, v112
	v_mul_f32_e32 v24, v25, v120
	v_mul_f32_e32 v25, v26, v113
	v_cvt_pk_bf16_f32 v18, v2, v18
	v_cvt_pk_bf16_f32 v19, v19, v20
	v_cvt_pk_bf16_f32 v20, v21, v22
	v_cvt_pk_bf16_f32 v21, v23, v24
	v_mul_f32_e32 v26, v27, v121
	v_mul_f32_e32 v27, v28, v114
	v_mul_f32_e32 v28, v29, v122
	v_mul_f32_e32 v29, v30, v115
	v_mul_f32_e32 v30, v31, v123
	v_mul_f32_e32 v31, v32, v116
	v_mul_f32_e32 v32, v33, v124
	v_cvt_pk_bf16_f32 v22, v25, v26
	v_cvt_pk_bf16_f32 v23, v27, v28
	v_cvt_pk_bf16_f32 v24, v29, v30
	v_cvt_pk_bf16_f32 v25, v31, v32
	global_store_dwordx4 v[110:111], v[18:21], off
	global_store_dwordx4 v[110:111], v[22:25], off offset:16
	s_cbranch_scc1 .LBB0_3032
